# c20 + prompt cumsum WGs skip 12 pass-A rounds (two more receivers)
# speedup vs baseline: 1.0014x; 1.0014x over previous
.LBB0_357:
	s_add_u32 s0, s76, 0x10243500
	v_writelane_b32 v255, s0, 7
	s_addc_u32 s0, s77, 0
	v_writelane_b32 v255, s0, 8
	s_add_u32 s0, s76, 0x8100000
	v_readlane_b32 s4, v254, 34
	v_writelane_b32 v255, s0, 9
	s_addc_u32 s0, s77, 0
	s_lshl_b32 s5, s80, 4
	s_and_b32 s28, s4, 0xffffffc0
	v_writelane_b32 v255, s0, 10
	s_add_u32 s0, s76, 0x10100000
	v_writelane_b32 v255, s0, 1
	s_addc_u32 s0, s77, 0
	v_writelane_b32 v255, s0, 3
	s_add_u32 s0, s76, 0x10343500
	v_writelane_b32 v255, s0, 4
	s_addc_u32 s0, s77, 0
	s_lshl_b32 s93, s80, 2
	v_writelane_b32 v255, s0, 11
	s_add_u32 s0, s78, 0xa81000
	v_writelane_b32 v255, s0, 12
	s_addc_u32 s0, s79, 0
	v_writelane_b32 v255, s0, 13
	s_add_u32 s0, s78, 0xb81000
	v_writelane_b32 v255, s0, 14
	s_addc_u32 s0, s79, 0
	v_writelane_b32 v255, s0, 15
	s_lshl_b32 s0, s80, 5
	s_and_b32 s23, s0, 32
	s_add_u32 s48, s78, 0x10c9000
	s_addc_u32 s49, s79, 0
	s_add_u32 s0, s78, 0x1e467000
	v_writelane_b32 v255, s0, 16
	s_addc_u32 s0, s79, 0
	v_readlane_b32 s52, v254, 2
	v_writelane_b32 v255, s0, 17
	s_add_u32 s0, s78, 0xc89000
	v_readlane_b32 s56, v254, 6
	v_readlane_b32 s57, v254, 7
	v_writelane_b32 v255, s0, 18
	s_addc_u32 s0, s79, 0
	s_lshl_b32 s22, s80, 3
	v_readlane_b32 s58, v254, 8
	v_readlane_b32 s59, v254, 9
	v_readlane_b32 s60, v254, 10
	v_readlane_b32 s61, v254, 11
	v_readlane_b32 s62, v254, 12
	v_readlane_b32 s63, v254, 13
	v_readlane_b32 s64, v254, 14
	v_readlane_b32 s65, v254, 15
	v_readlane_b32 s66, v254, 16
	v_readlane_b32 s67, v254, 17
	s_mov_b64 s[8:9], s[56:57]
	v_writelane_b32 v255, s0, 19
	s_add_u32 s0, s8, 0x1800
	s_addc_u32 s1, s9, 0
	v_readlane_b32 s53, v254, 3
	v_readlane_b32 s54, v254, 4
	v_readlane_b32 s55, v254, 5
	v_writelane_b32 v254, s0, 51
	s_mov_b32 s3, 0xc300
	s_movk_i32 s85, 0x7ff
	v_writelane_b32 v254, s1, 52
	s_add_u32 s0, s8, 0x1000
	s_addc_u32 s1, s9, 0
	v_writelane_b32 v254, s0, 53
	s_and_b32 s29, s22, 0x1ffffff0
	s_waitcnt vmcnt(3)
	v_mbcnt_lo_u32_b32 v0, -1, 0
	v_writelane_b32 v254, s1, 54
	s_add_u32 s0, s78, 0x1cb31000
	v_writelane_b32 v254, s0, 55
	s_addc_u32 s0, s79, 0
	s_lshl_b32 s2, s80, 8
	v_writelane_b32 v254, s0, 57
	s_add_i32 s0, s2, 0x19600
	s_cmp_eq_u32 s80, 7
	v_writelane_b32 v254, s0, 59
	s_cselect_b64 s[0:1], -1, 0
	v_writelane_b32 v254, s0, 61
	v_mov_b32_e32 v1, 0
	s_mov_b32 s91, 0xbfb8aa3b
	v_writelane_b32 v254, s1, 62
	s_lshl_b32 s0, s80, 1
	s_and_b32 s0, s0, 2
	s_lshl_b32 s24, s0, 4
	s_lshl_b32 s0, s0, 6
	s_mov_b32 s51, s0
	s_or_b32 s0, s0, 0x1c700
	v_writelane_b32 v254, s0, 63
	s_cmpk_lt_u32 s4, 0x80
	v_readlane_b32 s0, v254, 42
	v_readlane_b32 s1, v254, 43
	s_cselect_b64 s[70:71], -1, 0
	s_and_b64 s[0:1], s[0:1], exec
	s_cselect_b32 s21, s3, 0x14500
	s_lshl_b32 s0, s80, 6
	s_add_i32 s0, s21, s0
	v_writelane_b32 v255, s0, 20
	s_add_u32 s0, s78, 0x18931000
	v_writelane_b32 v254, s0, 45
	s_addc_u32 s0, s79, 0
	v_writelane_b32 v254, s0, 47
	s_add_i32 s0, s80, -1
	s_bfe_u32 s35, s4, 0x30006
	s_cmp_gt_u32 s0, 6
	s_cselect_b64 s[72:73], -1, 0
	s_and_b32 s84, s80, 0x3fffff8
	s_cmp_lg_u32 s35, 0
	s_cselect_b64 s[30:31], -1, 0
	v_writelane_b32 v255, s5, 21
	s_add_i32 s0, s5, 0xfffff800
	v_writelane_b32 v255, s0, 22
	s_lshr_b32 s0, s4, 2
	s_and_b32 s0, s0, 0x3ffffff0
	v_writelane_b32 v255, s0, 23
	s_add_i32 s0, s28, 0xfffffe00
	v_writelane_b32 v255, s0, 24
	s_add_i32 s0, s2, 0x8200
	v_readlane_b32 s2, v254, 44
	v_writelane_b32 v255, s0, 25
	s_mov_b32 s68, 0xb2a5705f
	s_mov_b32 s69, 0x42ce8ed0
	s_mov_b32 s97, 0xc2b17218
	s_mov_b32 s81, 0x7f800000
	s_mov_b32 s34, 0x3f2aaaab
	v_mov_b32_e32 v112, 0x3ecc95a3
	s_mov_b32 s0, 0x33800000
	s_movk_i32 s1, 0xd40
	s_movk_i32 s25, 0x104
	s_mov_b32 s95, 0x800000
	v_mov_b32_e32 v113, 0x7f800000
	v_mov_b32_e32 v90, 0x3f317218
	v_mbcnt_hi_u32_b32 v114, -1, v0
	v_mov_b32_e32 v115, 0x41b17218
	v_mov_b32_e32 v116, 0x24900
	v_mov_b32_e32 v117, 0x900
	v_mov_b32_e32 v118, 0x20800
	s_mov_b32 s50, 0x3f317217
	s_mov_b32 s89, 0
	s_mov_b32 s90, 0x3e9b6dac
	s_mov_b32 s92, 0x3f317218
	s_mov_b32 s94, 0xb102e308
	s_mov_b32 s96, 0x3f2aaada
	s_mov_b32 s26, s2
	s_mov_b32 s3, 0
	s_cmpk_lg_u32 s20, 0x100
	s_cbranch_scc1 .Lp2_init_done
	s_and_b32 s3, s2, 0xfe
	s_cmpk_eq_u32 s3, 0x80
	s_cselect_b32 s3, 1, 0
	s_cbranch_scc1 .Lp2_init_done
	s_sub_u32 vcc_lo, s2, 0xa0
	s_cmp_lt_u32 vcc_lo, 2
	s_cbranch_scc0 .Lp2_init_n
	s_add_u32 s26, vcc_lo, 0x480
	s_mov_b32 s3, 2
	s_branch .Lp2_init_done
.Lp2_init_n:
	s_cmpk_lt_u32 s2, 0xa8
	s_cbranch_scc1 .Lp2_init_done
	s_and_b32 vcc_lo, s2, 6
	s_cmp_lg_u32 vcc_lo, 0
	s_cbranch_scc1 .Lp2_init_done
	s_sub_u32 vcc_lo, s2, 0xa8
	s_lshr_b32 vcc_lo, vcc_lo, 3
	s_cmp_ge_u32 vcc_lo, 11
	s_cbranch_scc1 .Lp2_init_done
	s_add_u32 vcc_lo, vcc_lo, 5
	s_lshl_b32 vcc_lo, vcc_lo, 8
	s_and_b32 s3, s2, 1
	s_add_u32 vcc_lo, vcc_lo, s3
	s_add_u32 s26, vcc_lo, 0x80
	s_mov_b32 s3, 2

.LBB0_359:
	v_readlane_b32 s2, v255, 40
	s_cmp_eq_u32 s2, 0
	s_cbranch_scc1 .Lp2_norm
	s_cmp_eq_u32 s2, 2
	s_cbranch_scc1 .Lp2_recv
	s_lshr_b32 s2, s26, 8
	s_cmp_eq_u32 s2, 3
	s_cbranch_scc0 .Lp2_norm
	s_addk_i32 s26, 3072
	s_branch .Lp2_norm
